# same barrier as previous, census post/read keyed on barrier ordinals (robustness only)
# baseline (speedup 1.0000x reference)
; __device__ __forceinline__ KArgs kargs() { auto p = __builtin_amdgcn_kernarg_segment_ptr(); asm volatile("" : "+s"(p)); return (KArgs)p; }
; __global__ void __launch_bounds__(512, 2) mega(Args a_unused) {
;     ...
;         if (ph + 1 < kargs()->hi) { if (kargs()->coop) cg::this_grid().sync(); }
.Lgs_noinit:
	s_mov_b64 exec, s[12:13]
	s_cmp_eq_u32 s100, 1
	s_cbranch_scc0 .Lgs_nocensus
	s_getreg_b32 s9, hwreg(HW_REG_XCC_ID, 0, 4)
	s_lshl_b32 s9, s9, 2
	s_add_u32 s10, s6, 0x337ff800
	s_addc_u32 s11, s7, 0
	s_add_u32 s10, s10, s9
	s_addc_u32 s11, s11, 0
	v_mov_b32_e32 v1, 1
	global_atomic_add v211, v1, s[10:11]

; __device__ __forceinline__ KArgs kargs() { auto p = __builtin_amdgcn_kernarg_segment_ptr(); asm volatile("" : "+s"(p)); return (KArgs)p; }
; __global__ void __launch_bounds__(512, 2) mega(Args a_unused) {
;     ...
;         if (ph + 1 < kargs()->hi) { if (kargs()->coop) cg::this_grid().sync(); }
.Lgs_hier:
	s_load_dwordx2 s[6:7], s[82:83], 0xa0
	s_getreg_b32 s11, hwreg(HW_REG_XCC_ID, 0, 4)
	s_add_i32 s101, s101, 1
	s_cmp_lg_u32 s101, 1
	s_cbranch_scc1 .Lgs_have_census
	s_waitcnt lgkmcnt(0)
	s_add_u32 s8, s6, 0x337ff800
	s_addc_u32 s9, s7, 0
	s_mov_b64 s[12:13], exec
	s_mov_b32 exec_lo, 0xffff
	s_mov_b32 exec_hi, 0
	v_mbcnt_lo_u32_b32 v0, -1, 0
	v_lshlrev_b32_e32 v1, 2, v0
	global_load_dword v1, v1, s[8:9] sc1
	s_waitcnt vmcnt(0)
	v_cmp_ne_u32_e32 vcc, 0, v1
	s_bcnt1_i32_b64 s10, vcc
	s_nop 3
	v_readlane_b32 s1, v1, s11
	s_mov_b64 exec, s[12:13]
	s_nop 0
	v_writelane_b32 v255, s1, 61
	v_writelane_b32 v255, s10, 62
